# mods_phase adaLN GEMV inner loop: 32 weight-row loads in flight per wave (SGPR base + lane offset) instead of serialized groups of 8
# speedup vs baseline: 1.0041x; 1.0030x over previous
.LBB0_63:
	s_mul_hi_i32 s4, s21, 0x2aaaaaab
	s_lshr_b32 s5, s4, 31
	s_ashr_i32 s4, s4, 4
	s_add_i32 s22, s4, s5
	s_mul_i32 s4, s22, 0x60
	s_sub_i32 s12, s21, s4
	s_mov_b32 s4, 4
	s_ashr_i32 s5, s4, 31
	s_lshl_b64 s[4:5], s[4:5], 3
	s_add_u32 s4, s0, s4
	s_addc_u32 s5, s1, s5
	s_load_dwordx2 s[4:5], s[4:5], 0x0
	v_lshl_or_b32 v6, s12, 6, v15
	v_ashrrev_i32_e32 v7, 31, v6
	v_lshlrev_b64 v[6:7], 2, v[6:7]
	s_mov_b64 s[12:13], 0
	s_waitcnt lgkmcnt(0)
	v_lshl_add_u64 v[8:9], s[4:5], 0, v[2:3]
	v_mad_i64_i32 v[10:11], s[4:5], s22, v14, v[6:7]
	v_lshl_add_u64 v[8:9], v[8:9], 0, v[10:11]
	v_mov_b32_e32 v10, 0
	v_mov_b32_e32 v18, v1
	v_mov_b32_e32 v11, v10
	v_mov_b32_e32 v12, v10
	v_mov_b32_e32 v13, v10
	v_mov_b32_e32 v19, v10
	v_readfirstlane_b32 s12, v8
	v_readfirstlane_b32 s13, v9
	v_lshlrev_b32_e32 v184, 2, v15
	s_mov_b32 s4, 0
	s_nop 3
.LBB0_64:
	global_load_dword v152, v184, s[12:13]
	s_add_u32 s12, s12, 0x6000
	s_addc_u32 s13, s13, 0
	global_load_dword v153, v184, s[12:13]
	s_add_u32 s12, s12, 0x6000
	s_addc_u32 s13, s13, 0
	global_load_dword v154, v184, s[12:13]
	s_add_u32 s12, s12, 0x6000
	s_addc_u32 s13, s13, 0
	global_load_dword v155, v184, s[12:13]
	s_add_u32 s12, s12, 0x6000
	s_addc_u32 s13, s13, 0
	global_load_dword v156, v184, s[12:13]
	s_add_u32 s12, s12, 0x6000
	s_addc_u32 s13, s13, 0
	global_load_dword v157, v184, s[12:13]
	s_add_u32 s12, s12, 0x6000
	s_addc_u32 s13, s13, 0
	global_load_dword v158, v184, s[12:13]
	s_add_u32 s12, s12, 0x6000
	s_addc_u32 s13, s13, 0
	global_load_dword v159, v184, s[12:13]
	s_add_u32 s12, s12, 0x6000
	s_addc_u32 s13, s13, 0
	global_load_dword v160, v184, s[12:13]
	s_add_u32 s12, s12, 0x6000
	s_addc_u32 s13, s13, 0
	global_load_dword v161, v184, s[12:13]
	s_add_u32 s12, s12, 0x6000
	s_addc_u32 s13, s13, 0
	global_load_dword v162, v184, s[12:13]
	s_add_u32 s12, s12, 0x6000
	s_addc_u32 s13, s13, 0
	global_load_dword v163, v184, s[12:13]
	s_add_u32 s12, s12, 0x6000
	s_addc_u32 s13, s13, 0
	global_load_dword v164, v184, s[12:13]
	s_add_u32 s12, s12, 0x6000
	s_addc_u32 s13, s13, 0
	global_load_dword v165, v184, s[12:13]
	s_add_u32 s12, s12, 0x6000
	s_addc_u32 s13, s13, 0
	global_load_dword v166, v184, s[12:13]
	s_add_u32 s12, s12, 0x6000
	s_addc_u32 s13, s13, 0
	global_load_dword v167, v184, s[12:13]
	s_add_u32 s12, s12, 0x6000
	s_addc_u32 s13, s13, 0
	global_load_dword v168, v184, s[12:13]
	s_add_u32 s12, s12, 0x6000
	s_addc_u32 s13, s13, 0
	global_load_dword v169, v184, s[12:13]
	s_add_u32 s12, s12, 0x6000
	s_addc_u32 s13, s13, 0
	global_load_dword v170, v184, s[12:13]
	s_add_u32 s12, s12, 0x6000
	s_addc_u32 s13, s13, 0
	global_load_dword v171, v184, s[12:13]
	s_add_u32 s12, s12, 0x6000
	s_addc_u32 s13, s13, 0
	global_load_dword v172, v184, s[12:13]
	s_add_u32 s12, s12, 0x6000
	s_addc_u32 s13, s13, 0
	global_load_dword v173, v184, s[12:13]
	s_add_u32 s12, s12, 0x6000
	s_addc_u32 s13, s13, 0
	global_load_dword v174, v184, s[12:13]
	s_add_u32 s12, s12, 0x6000
	s_addc_u32 s13, s13, 0
	global_load_dword v175, v184, s[12:13]
	s_add_u32 s12, s12, 0x6000
	s_addc_u32 s13, s13, 0
	global_load_dword v176, v184, s[12:13]
	s_add_u32 s12, s12, 0x6000
	s_addc_u32 s13, s13, 0
	global_load_dword v177, v184, s[12:13]
	s_add_u32 s12, s12, 0x6000
	s_addc_u32 s13, s13, 0
	global_load_dword v178, v184, s[12:13]
	s_add_u32 s12, s12, 0x6000
	s_addc_u32 s13, s13, 0
	global_load_dword v179, v184, s[12:13]
	s_add_u32 s12, s12, 0x6000
	s_addc_u32 s13, s13, 0
	global_load_dword v180, v184, s[12:13]
	s_add_u32 s12, s12, 0x6000
	s_addc_u32 s13, s13, 0
	global_load_dword v181, v184, s[12:13]
	s_add_u32 s12, s12, 0x6000
	s_addc_u32 s13, s13, 0
	global_load_dword v182, v184, s[12:13]
	s_add_u32 s12, s12, 0x6000
	s_addc_u32 s13, s13, 0
	global_load_dword v183, v184, s[12:13]
	s_add_u32 s12, s12, 0x6000
	s_addc_u32 s13, s13, 0
	ds_read_b128 v[20:23], v18
	ds_read_b128 v[24:27], v18 offset:16
	ds_read_b128 v[28:31], v18 offset:4096
	ds_read_b128 v[32:35], v18 offset:4112
	ds_read_b128 v[36:39], v18 offset:8192
	ds_read_b128 v[40:43], v18 offset:8208
	ds_read_b128 v[44:47], v18 offset:12288
	ds_read_b128 v[48:51], v18 offset:12304
	ds_read_b128 v[52:55], v18 offset:16384
	ds_read_b128 v[56:59], v18 offset:16400
	s_waitcnt lgkmcnt(0)
	s_waitcnt vmcnt(31)
	v_fmac_f32_e32 v10, v152, v20
	v_fmac_f32_e32 v11, v152, v28
	v_fmac_f32_e32 v12, v152, v36
	v_fmac_f32_e32 v13, v152, v44
	v_fmac_f32_e32 v19, v152, v52
	s_waitcnt vmcnt(30)
	v_fmac_f32_e32 v10, v153, v21
	v_fmac_f32_e32 v11, v153, v29
	v_fmac_f32_e32 v12, v153, v37
	v_fmac_f32_e32 v13, v153, v45
	v_fmac_f32_e32 v19, v153, v53
	s_waitcnt vmcnt(29)
	v_fmac_f32_e32 v10, v154, v22
	v_fmac_f32_e32 v11, v154, v30
	v_fmac_f32_e32 v12, v154, v38
	v_fmac_f32_e32 v13, v154, v46
	v_fmac_f32_e32 v19, v154, v54
	s_waitcnt vmcnt(28)
	v_fmac_f32_e32 v10, v155, v23
	v_fmac_f32_e32 v11, v155, v31
	v_fmac_f32_e32 v12, v155, v39
	v_fmac_f32_e32 v13, v155, v47
	v_fmac_f32_e32 v19, v155, v55
	s_waitcnt vmcnt(27)
	v_fmac_f32_e32 v10, v156, v24
	v_fmac_f32_e32 v11, v156, v32
	v_fmac_f32_e32 v12, v156, v40
	v_fmac_f32_e32 v13, v156, v48
	v_fmac_f32_e32 v19, v156, v56
	s_waitcnt vmcnt(26)
	v_fmac_f32_e32 v10, v157, v25
	v_fmac_f32_e32 v11, v157, v33
	v_fmac_f32_e32 v12, v157, v41
	v_fmac_f32_e32 v13, v157, v49
	v_fmac_f32_e32 v19, v157, v57
	s_waitcnt vmcnt(25)
	v_fmac_f32_e32 v10, v158, v26
	v_fmac_f32_e32 v11, v158, v34
	v_fmac_f32_e32 v12, v158, v42
	v_fmac_f32_e32 v13, v158, v50
	v_fmac_f32_e32 v19, v158, v58
	s_waitcnt vmcnt(24)
	v_fmac_f32_e32 v10, v159, v27
	v_fmac_f32_e32 v11, v159, v35
	v_fmac_f32_e32 v12, v159, v43
	v_fmac_f32_e32 v13, v159, v51
	v_fmac_f32_e32 v19, v159, v59
	ds_read_b128 v[20:23], v18 offset:32
	ds_read_b128 v[24:27], v18 offset:48
	ds_read_b128 v[28:31], v18 offset:4128
	ds_read_b128 v[32:35], v18 offset:4144
	ds_read_b128 v[36:39], v18 offset:8224
	ds_read_b128 v[40:43], v18 offset:8240
	ds_read_b128 v[44:47], v18 offset:12320
	ds_read_b128 v[48:51], v18 offset:12336
	ds_read_b128 v[52:55], v18 offset:16416
	ds_read_b128 v[56:59], v18 offset:16432
	s_waitcnt lgkmcnt(0)
	s_waitcnt vmcnt(23)
	v_fmac_f32_e32 v10, v160, v20
	v_fmac_f32_e32 v11, v160, v28
	v_fmac_f32_e32 v12, v160, v36
	v_fmac_f32_e32 v13, v160, v44
	v_fmac_f32_e32 v19, v160, v52
	s_waitcnt vmcnt(22)
	v_fmac_f32_e32 v10, v161, v21
	v_fmac_f32_e32 v11, v161, v29
	v_fmac_f32_e32 v12, v161, v37
	v_fmac_f32_e32 v13, v161, v45
	v_fmac_f32_e32 v19, v161, v53
	s_waitcnt vmcnt(21)
	v_fmac_f32_e32 v10, v162, v22
	v_fmac_f32_e32 v11, v162, v30
	v_fmac_f32_e32 v12, v162, v38
	v_fmac_f32_e32 v13, v162, v46
	v_fmac_f32_e32 v19, v162, v54
	s_waitcnt vmcnt(20)
	v_fmac_f32_e32 v10, v163, v23
	v_fmac_f32_e32 v11, v163, v31
	v_fmac_f32_e32 v12, v163, v39
	v_fmac_f32_e32 v13, v163, v47
	v_fmac_f32_e32 v19, v163, v55
	s_waitcnt vmcnt(19)
	v_fmac_f32_e32 v10, v164, v24
	v_fmac_f32_e32 v11, v164, v32
	v_fmac_f32_e32 v12, v164, v40
	v_fmac_f32_e32 v13, v164, v48
	v_fmac_f32_e32 v19, v164, v56
	s_waitcnt vmcnt(18)
	v_fmac_f32_e32 v10, v165, v25
	v_fmac_f32_e32 v11, v165, v33
	v_fmac_f32_e32 v12, v165, v41
	v_fmac_f32_e32 v13, v165, v49
	v_fmac_f32_e32 v19, v165, v57
	s_waitcnt vmcnt(17)
	v_fmac_f32_e32 v10, v166, v26
	v_fmac_f32_e32 v11, v166, v34
	v_fmac_f32_e32 v12, v166, v42
	v_fmac_f32_e32 v13, v166, v50
	v_fmac_f32_e32 v19, v166, v58
	s_waitcnt vmcnt(16)
	v_fmac_f32_e32 v10, v167, v27
	v_fmac_f32_e32 v11, v167, v35
	v_fmac_f32_e32 v12, v167, v43
	v_fmac_f32_e32 v13, v167, v51
	v_fmac_f32_e32 v19, v167, v59
	ds_read_b128 v[20:23], v18 offset:64
	ds_read_b128 v[24:27], v18 offset:80
	ds_read_b128 v[28:31], v18 offset:4160
	ds_read_b128 v[32:35], v18 offset:4176
	ds_read_b128 v[36:39], v18 offset:8256
	ds_read_b128 v[40:43], v18 offset:8272
	ds_read_b128 v[44:47], v18 offset:12352
	ds_read_b128 v[48:51], v18 offset:12368
	ds_read_b128 v[52:55], v18 offset:16448
	ds_read_b128 v[56:59], v18 offset:16464
	s_waitcnt lgkmcnt(0)
	s_waitcnt vmcnt(15)
	v_fmac_f32_e32 v10, v168, v20
	v_fmac_f32_e32 v11, v168, v28
	v_fmac_f32_e32 v12, v168, v36
	v_fmac_f32_e32 v13, v168, v44
	v_fmac_f32_e32 v19, v168, v52
	s_waitcnt vmcnt(14)
	v_fmac_f32_e32 v10, v169, v21
	v_fmac_f32_e32 v11, v169, v29
	v_fmac_f32_e32 v12, v169, v37
	v_fmac_f32_e32 v13, v169, v45
	v_fmac_f32_e32 v19, v169, v53
	s_waitcnt vmcnt(13)
	v_fmac_f32_e32 v10, v170, v22
	v_fmac_f32_e32 v11, v170, v30
	v_fmac_f32_e32 v12, v170, v38
	v_fmac_f32_e32 v13, v170, v46
	v_fmac_f32_e32 v19, v170, v54
	s_waitcnt vmcnt(12)
	v_fmac_f32_e32 v10, v171, v23
	v_fmac_f32_e32 v11, v171, v31
	v_fmac_f32_e32 v12, v171, v39
	v_fmac_f32_e32 v13, v171, v47
	v_fmac_f32_e32 v19, v171, v55
	s_waitcnt vmcnt(11)
	v_fmac_f32_e32 v10, v172, v24
	v_fmac_f32_e32 v11, v172, v32
	v_fmac_f32_e32 v12, v172, v40
	v_fmac_f32_e32 v13, v172, v48
	v_fmac_f32_e32 v19, v172, v56
	s_waitcnt vmcnt(10)
	v_fmac_f32_e32 v10, v173, v25
	v_fmac_f32_e32 v11, v173, v33
	v_fmac_f32_e32 v12, v173, v41
	v_fmac_f32_e32 v13, v173, v49
	v_fmac_f32_e32 v19, v173, v57
	s_waitcnt vmcnt(9)
	v_fmac_f32_e32 v10, v174, v26
	v_fmac_f32_e32 v11, v174, v34
	v_fmac_f32_e32 v12, v174, v42
	v_fmac_f32_e32 v13, v174, v50
	v_fmac_f32_e32 v19, v174, v58
	s_waitcnt vmcnt(8)
	v_fmac_f32_e32 v10, v175, v27
	v_fmac_f32_e32 v11, v175, v35
	v_fmac_f32_e32 v12, v175, v43
	v_fmac_f32_e32 v13, v175, v51
	v_fmac_f32_e32 v19, v175, v59
	ds_read_b128 v[20:23], v18 offset:96
	ds_read_b128 v[24:27], v18 offset:112
	ds_read_b128 v[28:31], v18 offset:4192
	ds_read_b128 v[32:35], v18 offset:4208
	ds_read_b128 v[36:39], v18 offset:8288
	ds_read_b128 v[40:43], v18 offset:8304
	ds_read_b128 v[44:47], v18 offset:12384
	ds_read_b128 v[48:51], v18 offset:12400
	ds_read_b128 v[52:55], v18 offset:16480
	ds_read_b128 v[56:59], v18 offset:16496
	s_waitcnt lgkmcnt(0)
	s_waitcnt vmcnt(7)
	v_fmac_f32_e32 v10, v176, v20
	v_fmac_f32_e32 v11, v176, v28
	v_fmac_f32_e32 v12, v176, v36
	v_fmac_f32_e32 v13, v176, v44
	v_fmac_f32_e32 v19, v176, v52
	s_waitcnt vmcnt(6)
	v_fmac_f32_e32 v10, v177, v21
	v_fmac_f32_e32 v11, v177, v29
	v_fmac_f32_e32 v12, v177, v37
	v_fmac_f32_e32 v13, v177, v45
	v_fmac_f32_e32 v19, v177, v53
	s_waitcnt vmcnt(5)
	v_fmac_f32_e32 v10, v178, v22
	v_fmac_f32_e32 v11, v178, v30
	v_fmac_f32_e32 v12, v178, v38
	v_fmac_f32_e32 v13, v178, v46
	v_fmac_f32_e32 v19, v178, v54
	s_waitcnt vmcnt(4)
	v_fmac_f32_e32 v10, v179, v23
	v_fmac_f32_e32 v11, v179, v31
	v_fmac_f32_e32 v12, v179, v39
	v_fmac_f32_e32 v13, v179, v47
	v_fmac_f32_e32 v19, v179, v55
	s_waitcnt vmcnt(3)
	v_fmac_f32_e32 v10, v180, v24
	v_fmac_f32_e32 v11, v180, v32
	v_fmac_f32_e32 v12, v180, v40
	v_fmac_f32_e32 v13, v180, v48
	v_fmac_f32_e32 v19, v180, v56
	s_waitcnt vmcnt(2)
	v_fmac_f32_e32 v10, v181, v25
	v_fmac_f32_e32 v11, v181, v33
	v_fmac_f32_e32 v12, v181, v41
	v_fmac_f32_e32 v13, v181, v49
	v_fmac_f32_e32 v19, v181, v57
	s_waitcnt vmcnt(1)
	v_fmac_f32_e32 v10, v182, v26
	v_fmac_f32_e32 v11, v182, v34
	v_fmac_f32_e32 v12, v182, v42
	v_fmac_f32_e32 v13, v182, v50
	v_fmac_f32_e32 v19, v182, v58
	s_waitcnt vmcnt(0)
	v_fmac_f32_e32 v10, v183, v27
	v_fmac_f32_e32 v11, v183, v35
	v_fmac_f32_e32 v12, v183, v43
	v_fmac_f32_e32 v13, v183, v51
	v_fmac_f32_e32 v19, v183, v59
	v_add_u32_e32 v18, 128, v18
	s_add_i32 s4, s4, 1
	s_cmp_eq_u32 s4, 4
	s_cbranch_scc0 .LBB0_64
	ds_write2st64_b32 v16, v10, v11 offset0:80 offset1:81
	ds_write2st64_b32 v16, v12, v13 offset0:82 offset1:83
	ds_write_b32 v16, v19 offset:21504
	s_waitcnt lgkmcnt(0)
	s_barrier
	s_and_saveexec_b64 s[4:5], vcc
	s_cbranch_execz .LBB0_62
	s_mul_i32 s12, s22, 0x6000
	s_mul_hi_i32 s13, s22, 0x6000
	s_add_u32 s12, s10, s12
	s_addc_u32 s13, s11, s13
	v_lshl_add_u64 v[8:9], s[12:13], 0, v[6:7]
	global_load_dword v24, v[8:9], off
	ds_read2st64_b32 v[8:9], v17 offset0:80 offset1:85
	ds_read2st64_b32 v[10:11], v17 offset0:90 offset1:95
	ds_read2st64_b32 v[12:13], v17 offset0:100 offset1:105
	ds_read2st64_b32 v[18:19], v17 offset0:110 offset1:115
	v_mad_i64_i32 v[20:21], s[12:13], s22, 5, v[4:5]
	s_waitcnt lgkmcnt(3)
	v_add_f32_e32 v8, 0, v8
	v_add_f32_e32 v8, v8, v9
	s_waitcnt lgkmcnt(2)
	v_add_f32_e32 v8, v8, v10
	v_add_f32_e32 v8, v8, v11
	s_waitcnt lgkmcnt(1)
	v_add_f32_e32 v8, v8, v12
	v_mov_b64_e32 v[22:23], s[8:9]
	v_add_f32_e32 v8, v8, v13
	v_mad_u64_u32 v[22:23], s[12:13], v20, s14, v[22:23]
	s_waitcnt lgkmcnt(0)
	v_add_f32_e32 v8, v8, v18
	v_mad_i32_i24 v23, v21, s14, v23
	v_add_f32_e32 v8, v8, v19
	v_lshl_add_u64 v[6:7], v[22:23], 0, v[6:7]
	s_waitcnt vmcnt(0)
	v_add_f32_e32 v8, v8, v24
	global_store_dword v[6:7], v8, off
	s_branch .LBB0_62
